# scan phase: a wave's second (sample-row) task reuses the first task's per-head constants and weight fragments instead of reloading them
# baseline (speedup 1.0000x reference)
; #define LDS_WAIT() asm volatile("s_waitcnt lgkmcnt(0)" ::: "memory")
; __device__ __forceinline__ void scan_phase(KP p, int l, LAS unsigned char* lds) {
;     ...
;     for (int task = gw; task < NTASK; task += NGW) {
;         const int head = task & 15, ck = task >> 4, hc0 = head * 64;
;         LDS_WAIT();
;         {
;             const int ch = hc0 + lane;
; #pragma unroll
;             for (int k = 0; k < 4; ++k) CST[k * 64 + lane] = p->in[14][(size_t)(l * 4 + k) * D + ch];
;             CST[4 * 64 + lane] = p->in[15][l * D + ch]; CST[5 * 64 + lane] = p->in[17][l * D + ch]; CST[6 * 64 + lane] = p->in[19][l * D + ch]; CST[7 * 64 + lane] = SP[ch];
;         }
;         bf16x8 Wa[4][2], Wx[4][2];
; #pragma unroll
;         for (int n = 0; n < 4; ++n)
; #pragma unroll
;             for (int s = 0; s < 2; ++s) { const size_t o = (size_t)head * 4096 + (16 * n + fr) * 64 + 32 * s + 8 * fq;
;                 Wa[n][s] = *(const bf16x8*)((const bf16_t*)(p->ws + WS_RGA) + o); Wx[n][s] = *(const bf16x8*)((const bf16_t*)(p->ws + WS_RGX) + o); }
;         if (ck < 128) {
.LBB0_331:
	s_cmpk_lt_u32 s54, 0x800
	s_cbranch_scc1 .Lscan_full_pro
	s_and_b32 s16, s54, 15
	s_lshl_b32 s75, s16, 6
	v_lshl_or_b32 v0, s16, 13, v238
	v_or_b32_e32 v0, 0x1840, v0
	global_load_dwordx4 v[2:5], v0, s[72:73]
	v_add_u32_e32 v241, v232, v231
	s_mov_b64 s[10:11], -1
	s_ashr_i32 s74, s54, 4
	v_lshlrev_b32_e32 v0, 1, v206
	s_cmpk_gt_i32 s74, 0x7f
	s_branch .Lscan_pro_done

; #define LAS __attribute__((address_space(3)))
; #define LDS_WAIT() asm volatile("s_waitcnt lgkmcnt(0)" ::: "memory")
; __device__ __forceinline__ void scan_phase(KP p, int l, LAS unsigned char* lds) {
;     ...
;             const int m0 = (1032 + (ck - 128)) * 16;
;             LDS_WAIT();
;             {   const int rr = lane >> 2, cb = lane & 3, cl = cb * 16, m = m0 + rr, sb = m - MP;
;                 float xv[4][16];
;                 const float* st = p->in[3] + ((size_t)(l * MS + sb) * 3) * D + hc0 + cl;
; #pragma unroll
;                 for (int k = 0; k < 3; ++k)
; #pragma unroll
;                     for (int e = 0; e < 16; e += 4) { const f32x4 v = *(const f32x4*)(st + (size_t)k * D + e); xv[k][e] = v[0]; xv[k][e + 1] = v[1]; xv[k][e + 2] = v[2]; xv[k][e + 3] = v[3]; }
;                 const bf16_t* src = P + (size_t)m * DP + C_XR + hc0 + cl;
;                 float f0[8], f1[8]; unpack8(*(const u32x4*)src, f0); unpack8(*(const u32x4*)(src + 8), f1);
; #pragma unroll
;                 for (int e = 0; e < 8; ++e) { xv[3][e] = f0[e]; xv[3][8 + e] = f1[e]; }
;                 float* o = p->out + O_SCB + ((size_t)(l * MS + sb) * 3) * D + hc0 + cl;
; #pragma unroll
;                 for (int k = 0; k < 3; ++k)
; #pragma unroll
;                     for (int e = 0; e < 16; e += 4) *(f32x4*)(o + (size_t)k * D + e) = (f32x4){xv[k + 1][e], xv[k + 1][e + 1], xv[k + 1][e + 2], xv[k + 1][e + 3]};
; #pragma unroll
;                 for (int e = 0; e < 16; e += 4) {
;                     const f32x4 w0 = *(const LAS f32x4*)(CST + 0 * 64 + cl + e), w1 = *(const LAS f32x4*)(CST + 1 * 64 + cl + e), w2 = *(const LAS f32x4*)(CST + 2 * 64 + cl + e),
;                                 w3 = *(const LAS f32x4*)(CST + 3 * 64 + cl + e), bb = *(const LAS f32x4*)(CST + 4 * 64 + cl + e);
;                     f32x4 r;
; #pragma unroll
;                     for (int q = 0; q < 4; ++q) r[q] = w0[q] * xv[0][e + q] + w1[q] * xv[1][e + q] + w2[q] * xv[2][e + q] + w3[q] * xv[3][e + q] + bb[q];
;                     *(LAS f32x4*)(XC + rr * 68 + cl + e) = r;
;                 }
;             }
.Lscan_pro_done:
	s_cbranch_scc0 .LBB0_333
	s_waitcnt lgkmcnt(0)
	s_load_dwordx4 s[12:15], s[58:59], 0x18
	s_and_b32 s10, s54, -16
	s_add_i32 s11, s10, 0x3880
	v_or_b32_e32 v106, s11, v226
	v_add_u32_e32 v126, s78, v106
	s_waitcnt lgkmcnt(0)
	v_mov_b64_e32 v[66:67], s[12:13]
	v_mad_i64_i32 v[66:67], s[12:13], v126, s23, v[66:67]
	s_lshl_b32 s16, s75, 2
	v_lshl_add_u64 v[66:67], v[66:67], 0, s[16:17]
	v_lshlrev_b32_e32 v122, 2, v206
	v_mov_b32_e32 v123, v1
	v_lshl_add_u64 v[70:71], v[66:67], 0, v[122:123]
	v_add_co_u32_e32 v78, vcc, s43, v70
	v_lshl_add_u64 v[72:73], v[70:71], 0, s[28:29]
	s_nop 0
	v_addc_co_u32_e32 v79, vcc, 0, v71, vcc
	global_load_dwordx4 v[66:69], v[70:71], off offset:48
	global_load_dwordx4 v[82:85], v[70:71], off offset:32
	global_load_dwordx4 v[94:97], v[70:71], off offset:16
	global_load_dwordx4 v[110:113], v[70:71], off
	global_load_dwordx4 v[114:117], v[78:79], off offset:-4096
	global_load_dwordx4 v[74:77], v[72:73], off offset:48
	global_load_dwordx4 v[90:93], v[72:73], off offset:32
	global_load_dwordx4 v[102:105], v[72:73], off offset:16
	v_lshl_add_u64 v[80:81], v[70:71], 0, s[30:31]
	global_load_dwordx4 v[118:121], v[78:79], off
	global_load_dwordx4 v[70:73], v[80:81], off offset:48
	global_load_dwordx4 v[86:89], v[80:81], off offset:32
	global_load_dwordx4 v[98:101], v[80:81], off offset:16
	v_mov_b64_e32 v[78:79], s[60:61]
	v_mad_u64_u32 v[78:79], s[12:13], v106, s33, v[78:79]
	s_lshl_b32 s12, s75, 1
	s_mov_b32 s13, s17
	v_lshl_add_u64 v[78:79], v[78:79], 0, s[12:13]
	v_lshl_add_u64 v[78:79], v[78:79], 0, v[0:1]
	v_lshl_add_u64 v[80:81], v[78:79], 0, s[28:29]
	v_add_co_u32_e32 v78, vcc, s38, v78
	s_nop 1
	v_addc_co_u32_e32 v79, vcc, 0, v79, vcc
	global_load_dwordx4 v[106:109], v[78:79], off
	s_nop 0
	global_load_dwordx4 v[78:81], v[80:81], off offset:16
	s_load_dwordx2 s[12:13], s[58:59], 0xe0
	s_waitcnt lgkmcnt(0)
	v_mov_b64_e32 v[124:125], s[12:13]
	v_mad_i64_i32 v[124:125], s[18:19], v126, s23, v[124:125]
	v_lshl_add_u64 v[124:125], v[124:125], 0, s[16:17]
	v_lshl_add_u64 v[146:147], v[124:125], 0, v[122:123]
	s_mov_b32 s16, 0x45f1000
	v_add_co_u32_e32 v124, vcc, s16, v146
	s_mov_b64 s[18:19], 0x45f0000
	s_nop 0
	v_addc_co_u32_e32 v125, vcc, 0, v147, vcc
	v_lshl_add_u64 v[122:123], v[146:147], 0, s[18:19]
	s_mov_b32 s16, 0x45f2000
	s_mov_b64 s[18:19], 0x4bf0000
	s_waitcnt vmcnt(9)
	global_store_dwordx4 v[124:125], v[114:117], off offset:-4096
	s_waitcnt vmcnt(7)
	global_store_dwordx4 v[122:123], v[102:105], off offset:16
	global_store_dwordx4 v[122:123], v[90:93], off offset:32
	global_store_dwordx4 v[122:123], v[74:77], off offset:48
	s_waitcnt vmcnt(9)
	global_store_dwordx4 v[124:125], v[118:121], off
	s_waitcnt vmcnt(7)
	global_store_dwordx4 v[124:125], v[98:101], off offset:16
	global_store_dwordx4 v[124:125], v[86:89], off offset:32
	global_store_dwordx4 v[124:125], v[70:73], off offset:48
	ds_read_b128 v[122:125], v227 offset:8704
	ds_read_b128 v[126:129], v227 offset:8960
	ds_read_b128 v[130:133], v227 offset:9216
	ds_read_b128 v[134:137], v227 offset:9472
	ds_read_b128 v[138:141], v227 offset:9728
	s_waitcnt lgkmcnt(3)
	v_pk_mul_f32 v[116:117], v[116:117], v[128:129]
	v_pk_mul_f32 v[114:115], v[114:115], v[126:127]
	v_pk_fma_f32 v[112:113], v[112:113], v[124:125], v[116:117]
	v_pk_fma_f32 v[110:111], v[110:111], v[122:123], v[114:115]
	s_waitcnt lgkmcnt(2)
	v_pk_fma_f32 v[112:113], v[120:121], v[132:133], v[112:113]
	v_pk_fma_f32 v[110:111], v[118:119], v[130:131], v[110:111]
	s_waitcnt vmcnt(9)
	v_lshlrev_b32_e32 v142, 16, v106
	v_and_b32_e32 v143, 0xffff0000, v106
	v_lshlrev_b32_e32 v144, 16, v107
	v_and_b32_e32 v145, 0xffff0000, v107
	v_add_co_u32_e32 v106, vcc, s16, v146
	s_waitcnt lgkmcnt(1)
	v_pk_fma_f32 v[112:113], v[136:137], v[144:145], v[112:113]
	v_pk_fma_f32 v[110:111], v[134:135], v[142:143], v[110:111]
	v_addc_co_u32_e32 v107, vcc, 0, v147, vcc
	s_waitcnt lgkmcnt(0)
	v_pk_add_f32 v[112:113], v[140:141], v[112:113]
	v_pk_add_f32 v[110:111], v[138:139], v[110:111]
	global_store_dwordx4 v[106:107], v[142:145], off
	ds_write_b128 v228, v[110:113]
	ds_read_b128 v[110:113], v227 offset:8720
	ds_read_b128 v[114:117], v227 offset:8976
	ds_read_b128 v[118:121], v227 offset:9232
	ds_read_b128 v[122:125], v227 offset:9488
	ds_read_b128 v[126:129], v227 offset:9744
	v_lshlrev_b32_e32 v130, 16, v108
	s_waitcnt lgkmcnt(3)
	v_pk_mul_f32 v[104:105], v[104:105], v[116:117]
	v_pk_mul_f32 v[102:103], v[102:103], v[114:115]
	v_pk_fma_f32 v[96:97], v[96:97], v[112:113], v[104:105]
	v_pk_fma_f32 v[94:95], v[94:95], v[110:111], v[102:103]
	v_and_b32_e32 v131, 0xffff0000, v108
	v_lshlrev_b32_e32 v132, 16, v109
	v_and_b32_e32 v133, 0xffff0000, v109
	s_waitcnt lgkmcnt(2)
	v_pk_fma_f32 v[96:97], v[100:101], v[120:121], v[96:97]
	v_pk_fma_f32 v[94:95], v[98:99], v[118:119], v[94:95]
	s_waitcnt lgkmcnt(1)
	v_pk_fma_f32 v[96:97], v[124:125], v[132:133], v[96:97]
	v_pk_fma_f32 v[94:95], v[122:123], v[130:131], v[94:95]
	s_waitcnt lgkmcnt(0)
	v_pk_add_f32 v[96:97], v[128:129], v[96:97]
	v_pk_add_f32 v[94:95], v[126:127], v[94:95]
	global_store_dwordx4 v[106:107], v[130:133], off offset:16
	ds_write_b128 v228, v[94:97] offset:16
	ds_read_b128 v[94:97], v227 offset:8736
	ds_read_b128 v[98:101], v227 offset:8992
	ds_read_b128 v[102:105], v227 offset:9248
	ds_read_b128 v[108:111], v227 offset:9504
	ds_read_b128 v[112:115], v227 offset:9760
	s_waitcnt vmcnt(10)
	v_lshlrev_b32_e32 v116, 16, v78
	v_and_b32_e32 v117, 0xffff0000, v78
	v_lshlrev_b32_e32 v118, 16, v79
	v_and_b32_e32 v119, 0xffff0000, v79
	s_waitcnt lgkmcnt(3)
; #define LAS __attribute__((address_space(3)))
; __device__ __forceinline__ float sigmoidf_(float x) { return __builtin_amdgcn_rcpf(1.0f + __expf(-x)); }
; __device__ __forceinline__ void scan_phase(KP p, int l, LAS unsigned char* lds) {
;     ...
;                     for (int q = 0; q < 4; ++q) r[q] = w0[q] * xv[0][e + q] + w1[q] * xv[1][e + q] + w2[q] * xv[2][e + q] + w3[q] * xv[3][e + q] + bb[q];
;                     *(LAS f32x4*)(XC + rr * 68 + cl + e) = r;
;                 }
;             }
;             LDS_WAIT();
;             f32x4 ar[4], ai[4];
; #pragma unroll
;             for (int n = 0; n < 4; ++n) { ar[n] = (f32x4){0.f, 0.f, 0.f, 0.f}; ai[n] = (f32x4){0.f, 0.f, 0.f, 0.f}; }
; #pragma unroll
;             for (int s = 0; s < 2; ++s) {
;                 const f32x4 x0 = *(const LAS f32x4*)(XC + fr * 68 + 32 * s + 8 * fq), x1 = *(const LAS f32x4*)(XC + fr * 68 + 32 * s + 8 * fq + 4);
;                 u32x4 aw; aw.x = cvt_pk_bf16(x0[0], x0[1]); aw.y = cvt_pk_bf16(x0[2], x0[3]); aw.z = cvt_pk_bf16(x1[0], x1[1]); aw.w = cvt_pk_bf16(x1[2], x1[3]);
;                 const bf16x8 af = __builtin_bit_cast(bf16x8, aw);
; #pragma unroll
;                 for (int n = 0; n < 4; ++n) { ar[n] = __builtin_amdgcn_mfma_f32_16x16x32_bf16(af, Wa[n][s], ar[n], 0, 0, 0); ai[n] = __builtin_amdgcn_mfma_f32_16x16x32_bf16(af, Wx[n][s], ai[n], 0, 0, 0); }
;             }
; #pragma unroll
;             for (int n = 0; n < 4; ++n) {
;                 const int cc = 16 * n + fr, ch = hc0 + cc;
;                 const float ba = CST[5 * 64 + cc], bx = CST[6 * 64 + cc], sp = CST[7 * 64 + cc];
; #pragma unroll
;                 for (int j = 0; j < 4; ++j) {
;                     const float xc = XC[(4 * fq + j) * 68 + cc];
;                     const float r = sigmoidf_(ar[n][j] + ba), ig = sigmoidf_(ai[n][j] + bx);
;                     const float a = __expf(-8.0f * r * sp);
;                     const float mult = sqrtf(fmaxf(1.0f - a * a, 0.f));
;                     const int sb = m0 - MP + 4 * fq + j;
;                     const float h0 = p->in[4][(size_t)(l * MS + sb) * D + ch];
;                     const float h = a * h0 + mult * ig * xc;
;                     const size_t o = (size_t)(m0 + 4 * fq + j) * D + ch; HLOC[o] = (bf16_t)(cvt_pk_bf16(h, 0.f) & 0xffffu); PCUM[o] = 0;
;                     p->out[O_SRG + (size_t)(l * MS + sb) * D + ch] = h; }
	v_pk_mul_f32 v[78:79], v[92:93], v[100:101]
	v_pk_mul_f32 v[90:91], v[90:91], v[98:99]
	v_pk_fma_f32 v[78:79], v[84:85], v[96:97], v[78:79]
	v_pk_fma_f32 v[82:83], v[82:83], v[94:95], v[90:91]
	s_waitcnt lgkmcnt(2)
	v_pk_fma_f32 v[78:79], v[88:89], v[104:105], v[78:79]
	v_pk_fma_f32 v[82:83], v[86:87], v[102:103], v[82:83]
	s_waitcnt lgkmcnt(1)
	v_pk_fma_f32 v[78:79], v[110:111], v[118:119], v[78:79]
	v_pk_fma_f32 v[82:83], v[108:109], v[116:117], v[82:83]
	s_waitcnt lgkmcnt(0)
	v_pk_add_f32 v[84:85], v[114:115], v[78:79]
	v_pk_add_f32 v[82:83], v[112:113], v[82:83]
	global_store_dwordx4 v[106:107], v[116:119], off offset:32
	ds_write_b128 v228, v[82:85] offset:32
	ds_read_b128 v[82:85], v227 offset:8752
	ds_read_b128 v[86:89], v227 offset:9008
	ds_read_b128 v[90:93], v227 offset:9264
	ds_read_b128 v[94:97], v227 offset:9520
	ds_read_b128 v[98:101], v227 offset:9776
	v_lshlrev_b32_e32 v78, 16, v80
	s_waitcnt lgkmcnt(3)
	v_pk_mul_f32 v[76:77], v[76:77], v[88:89]
	v_pk_mul_f32 v[74:75], v[74:75], v[86:87]
	v_pk_fma_f32 v[68:69], v[68:69], v[84:85], v[76:77]
	v_pk_fma_f32 v[66:67], v[66:67], v[82:83], v[74:75]
	v_and_b32_e32 v79, 0xffff0000, v80
	v_lshlrev_b32_e32 v80, 16, v81
	v_and_b32_e32 v81, 0xffff0000, v81
	s_waitcnt lgkmcnt(2)
	v_pk_fma_f32 v[68:69], v[72:73], v[92:93], v[68:69]
	v_pk_fma_f32 v[66:67], v[70:71], v[90:91], v[66:67]
	s_waitcnt lgkmcnt(1)
	v_pk_fma_f32 v[68:69], v[96:97], v[80:81], v[68:69]
	v_pk_fma_f32 v[66:67], v[94:95], v[78:79], v[66:67]
	s_waitcnt lgkmcnt(0)
	v_pk_add_f32 v[68:69], v[100:101], v[68:69]
	v_pk_add_f32 v[66:67], v[98:99], v[66:67]
	global_store_dwordx4 v[106:107], v[78:81], off offset:48
	ds_write_b128 v228, v[66:69] offset:48
	s_waitcnt lgkmcnt(0)
	ds_read_b128 v[66:69], v239
	ds_read_b128 v[70:73], v239 offset:16
	s_waitcnt lgkmcnt(1)
	v_cvt_pk_bf16_f32 v66, v66, v67
	v_cvt_pk_bf16_f32 v67, v68, v69
	s_waitcnt lgkmcnt(0)
	v_cvt_pk_bf16_f32 v68, v70, v71
	v_cvt_pk_bf16_f32 v69, v72, v73
	ds_read_b128 v[86:89], v239 offset:128
	ds_read_b128 v[90:93], v239 offset:144
	v_mfma_f32_16x16x32_bf16 v[70:73], v[66:69], v[34:37], 0
	s_waitcnt lgkmcnt(1)
	v_cvt_pk_bf16_f32 v110, v86, v87
	v_cvt_pk_bf16_f32 v111, v88, v89
	s_waitcnt lgkmcnt(0)
	v_cvt_pk_bf16_f32 v112, v90, v91
	v_cvt_pk_bf16_f32 v113, v92, v93
	ds_read2st64_b32 v[120:121], v232 offset0:39 offset1:40
	ds_read_b32 v123, v232 offset:10496
	v_mfma_f32_16x16x32_bf16 v[94:97], v[110:113], v[10:13], v[70:73]
	v_or_b32_e32 v114, s11, v229
	v_or_b32_e32 v122, s75, v223
	v_lshlrev_b32_e32 v116, 2, v122
	v_mfma_f32_16x16x32_bf16 v[78:81], v[66:69], v[42:45], 0
	v_mov_b32_e32 v117, v1
	s_waitcnt lgkmcnt(1)
	s_nop 1
	v_add_f32_e32 v94, v94, v120
	v_mul_f32_e32 v94, 0xbfb8aa3b, v94
	v_exp_f32_e32 v94, v94
	v_mfma_f32_16x16x32_bf16 v[98:101], v[66:69], v[50:53], 0
	v_lshl_add_u64 v[118:119], s[14:15], 0, v[116:117]
	v_ashrrev_i32_e32 v115, 31, v114
	v_add_f32_e32 v94, 1.0, v94
	v_rcp_f32_e32 v94, v94
	v_mfma_f32_16x16x32_bf16 v[86:89], v[110:113], v[22:25], v[78:81]
	v_mul_f32_e32 v94, 0xc1000000, v94
	s_waitcnt lgkmcnt(0)
	v_mul_f32_e32 v94, v123, v94
	v_mul_f32_e32 v94, 0x3fb8aa3b, v94
	v_exp_f32_e32 v94, v94
	v_mfma_f32_16x16x32_bf16 v[78:81], v[110:113], v[30:33], v[98:101]
	s_nop 2
	v_fma_f32 v98, -v94, v94, 1.0
	v_max_f32_e32 v98, 0, v98
	s_nop 0
	s_nop 0
	v_mfma_f32_16x16x32_bf16 v[74:77], v[66:69], v[38:41], 0
	ds_read_b32 v100, v241
	v_mfma_f32_16x16x32_bf16 v[102:105], v[66:69], v[54:57], 0
	s_nop 0
	v_mfma_f32_16x16x32_bf16 v[82:85], v[66:69], v[46:49], 0
	v_mfma_f32_16x16x32_bf16 v[106:109], v[66:69], v[62:65], 0
	v_mfma_f32_16x16x32_bf16 v[66:69], v[66:69], v[58:61], 0
	v_mfma_f32_16x16x32_bf16 v[90:93], v[110:113], v[14:17], v[74:77]
	v_mfma_f32_16x16x32_bf16 v[74:77], v[110:113], v[18:21], v[102:105]
	s_nop 2
	s_nop 0
	v_mfma_f32_16x16x32_bf16 v[82:85], v[110:113], v[26:29], v[82:85]
	s_nop 1
	v_add_f32_e32 v90, v90, v121
	v_mul_f32_e32 v90, 0xbfb8aa3b, v90
	v_exp_f32_e32 v90, v90
	v_mfma_f32_16x16x32_bf16 v[70:73], v[110:113], v[6:9], v[106:109]
	v_add_f32_e32 v91, v91, v121
	v_mul_f32_e32 v91, 0xbfb8aa3b, v91
	v_add_f32_e32 v90, 1.0, v90
	v_mfma_f32_16x16x32_bf16 v[66:69], v[110:113], v[2:5], v[66:69]
	v_add_u32_e32 v110, s10, v230
	v_ashrrev_i32_e32 v111, 31, v110
	v_lshlrev_b64 v[106:107], 12, v[110:111]
	v_rcp_f32_e32 v90, v90
	v_lshlrev_b64 v[102:103], 10, v[114:115]
	v_exp_f32_e32 v91, v91
	v_sqrt_f32_e32 v101, v98
	s_nop 0
	v_lshl_add_u64 v[98:99], v[118:119], 0, v[106:107]
	s_mov_b64 s[98:99], 0x1000
	v_lshl_add_u64 v[164:165], v[98:99], 0, s[98:99]
	s_mov_b64 s[98:99], 0x2000
	v_lshl_add_u64 v[166:167], v[98:99], 0, s[98:99]
	s_mov_b64 s[98:99], 0x3000
	v_lshl_add_u64 v[168:169], v[98:99], 0, s[98:99]
	global_load_dword v148, v[98:99], off
	global_load_dword v149, v[164:165], off
	global_load_dword v150, v[166:167], off
	global_load_dword v151, v[168:169], off
	global_load_dword v152, v[98:99], off offset:64
	global_load_dword v153, v[164:165], off offset:64
	global_load_dword v154, v[166:167], off offset:64
	global_load_dword v155, v[168:169], off offset:64
	global_load_dword v156, v[98:99], off offset:128
	global_load_dword v157, v[164:165], off offset:128
	global_load_dword v158, v[166:167], off offset:128
	global_load_dword v159, v[168:169], off offset:128
	global_load_dword v160, v[98:99], off offset:192
	global_load_dword v161, v[164:165], off offset:192
	global_load_dword v162, v[166:167], off offset:192
	global_load_dword v163, v[168:169], off offset:192
	v_mul_f32_e32 v90, v90, v101
	s_waitcnt lgkmcnt(0)
; __device__ __forceinline__ unsigned cvt_pk_bf16(float lo, float hi) { unsigned r; asm volatile("v_cvt_pk_bf16_f32 %0, %1, %2" : "=v"(r) : "v"(lo), "v"(hi)); return r; }
; __device__ __forceinline__ float sigmoidf_(float x) { return __builtin_amdgcn_rcpf(1.0f + __expf(-x)); }
; __device__ __forceinline__ void scan_phase(KP p, int l, LAS unsigned char* lds) {
;     ...
; #pragma unroll
;             for (int n = 0; n < 4; ++n) {
;                 const int cc = 16 * n + fr, ch = hc0 + cc;
;                 const float ba = CST[5 * 64 + cc], bx = CST[6 * 64 + cc], sp = CST[7 * 64 + cc];
; #pragma unroll
;                 for (int j = 0; j < 4; ++j) {
;                     const float xc = XC[(4 * fq + j) * 68 + cc];
;                     const float r = sigmoidf_(ar[n][j] + ba), ig = sigmoidf_(ai[n][j] + bx);
;                     const float a = __expf(-8.0f * r * sp);
;                     const float mult = sqrtf(fmaxf(1.0f - a * a, 0.f));
;                     const int sb = m0 - MP + 4 * fq + j;
;                     const float h0 = p->in[4][(size_t)(l * MS + sb) * D + ch];
;                     const float h = a * h0 + mult * ig * xc;
;                     const size_t o = (size_t)(m0 + 4 * fq + j) * D + ch; HLOC[o] = (bf16_t)(cvt_pk_bf16(h, 0.f) & 0xffffu); PCUM[o] = 0;
;                     p->out[O_SRG + (size_t)(l * MS + sb) * D + ch] = h; }
	v_mul_f32_e32 v90, v100, v90
	v_mov_b32_e32 v99, v103
	v_add_f32_e32 v91, 1.0, v91
	v_add_f32_e32 v92, v92, v121
	v_mul_f32_e32 v92, 0xbfb8aa3b, v92
	v_exp_f32_e32 v92, v92
	v_add_f32_e32 v93, v93, v121
	v_mul_f32_e32 v93, 0xbfb8aa3b, v93
	v_exp_f32_e32 v93, v93
	v_add_f32_e32 v92, 1.0, v92
	v_rcp_f32_e32 v92, v92
	v_add_f32_e32 v93, 1.0, v93
	s_waitcnt vmcnt(15)
	v_mov_b32_e32 v98, v148
	v_fmac_f32_e32 v90, v98, v94
	v_or_b32_e32 v98, v102, v122
	v_lshlrev_b64 v[98:99], 1, v[98:99]
	v_lshl_add_u64 v[100:101], v[98:99], 1, s[62:63]
	v_cvt_pk_bf16_f32 v94, v90, v1
	v_lshl_add_u64 v[98:99], s[12:13], 0, v[106:107]
	v_lshl_add_u64 v[98:99], v[98:99], 0, s[18:19]
	global_store_dword v[100:101], v94, off
	v_lshl_add_u64 v[100:101], v[98:99], 0, v[116:117]
	global_store_dword v[100:101], v90, off
	v_add_f32_e32 v90, v95, v120
	v_mul_f32_e32 v90, 0xbfb8aa3b, v90
	v_exp_f32_e32 v90, v90
	v_rcp_f32_e32 v95, v91
	ds_read_b32 v94, v241 offset:272
	v_add_f32_e32 v90, 1.0, v90
	v_rcp_f32_e32 v90, v90
	s_nop 0
	v_mul_f32_e32 v90, 0xc1000000, v90
	v_mul_f32_e32 v90, v123, v90
	v_mul_f32_e32 v90, 0x3fb8aa3b, v90
	v_exp_f32_e32 v100, v90
	s_nop 0
	v_fma_f32 v90, -v100, v100, 1.0
	v_max_f32_e32 v90, 0, v90
	s_nop 0
	s_nop 0
	s_nop 0
	s_nop 1
	s_nop 1
	v_sqrt_f32_e32 v101, v90
	s_nop 0
	v_or_b32_e32 v90, 1, v110
	v_ashrrev_i32_e32 v91, 31, v90
	v_lshlrev_b64 v[112:113], 12, v[90:91]
	v_lshl_add_u64 v[90:91], v[118:119], 0, v[112:113]
	v_mul_f32_e32 v91, v95, v101
	s_waitcnt lgkmcnt(0)
	v_mul_f32_e32 v104, v94, v91
	s_waitcnt vmcnt(16)
	v_mov_b32_e32 v90, v149
	v_fmac_f32_e32 v104, v100, v90
	v_or_b32_e32 v90, 1, v114
	v_ashrrev_i32_e32 v91, 31, v90
	v_lshlrev_b64 v[100:101], 10, v[90:91]
	v_or_b32_e32 v90, v100, v122
	v_mov_b32_e32 v91, v101
	v_lshlrev_b64 v[90:91], 1, v[90:91]
	v_lshl_add_u64 v[94:95], v[90:91], 1, s[62:63]
	v_cvt_pk_bf16_f32 v105, v104, v1
	v_lshl_add_u64 v[90:91], s[12:13], 0, v[112:113]
	v_lshl_add_u64 v[90:91], v[90:91], 0, s[18:19]
	global_store_dword v[94:95], v105, off
	v_lshl_add_u64 v[94:95], v[90:91], 0, v[116:117]
	global_store_dword v[94:95], v104, off
	v_add_f32_e32 v94, v96, v120
	v_mul_f32_e32 v94, 0xbfb8aa3b, v94
	v_exp_f32_e32 v94, v94
	ds_read_b32 v104, v241 offset:544
	v_add_f32_e32 v94, 1.0, v94
	v_rcp_f32_e32 v94, v94
	s_nop 0
	v_mul_f32_e32 v94, 0xc1000000, v94
	v_mul_f32_e32 v94, v123, v94
	v_mul_f32_e32 v94, 0x3fb8aa3b, v94
	v_exp_f32_e32 v96, v94
	s_nop 0
	v_fma_f32 v94, -v96, v96, 1.0
	v_max_f32_e32 v94, 0, v94
	s_nop 0
	s_nop 0
	s_nop 0
	s_nop 1
	s_nop 1
	v_sqrt_f32_e32 v105, v94
	s_nop 0
	v_or_b32_e32 v94, 2, v110
	v_ashrrev_i32_e32 v95, 31, v94
	v_lshlrev_b64 v[108:109], 12, v[94:95]
	v_lshl_add_u64 v[94:95], v[118:119], 0, v[108:109]
	v_mul_f32_e32 v92, v92, v105
	s_waitcnt vmcnt(17)
	v_mov_b32_e32 v94, v150
	v_mul_f32_e32 v96, v96, v94
	v_or_b32_e32 v94, 2, v114
	v_ashrrev_i32_e32 v95, 31, v94
	s_waitcnt lgkmcnt(0)
	v_fmac_f32_e32 v96, v92, v104
	v_lshlrev_b64 v[104:105], 10, v[94:95]
	v_or_b32_e32 v94, v104, v122
	v_mov_b32_e32 v95, v105
	v_lshlrev_b64 v[94:95], 1, v[94:95]
	v_cvt_pk_bf16_f32 v92, v96, v1
	v_lshl_add_u64 v[124:125], v[94:95], 1, s[62:63]
	global_store_dword v[124:125], v92, off
	v_add_f32_e32 v92, v97, v120
	v_mul_f32_e32 v92, 0xbfb8aa3b, v92
	v_exp_f32_e32 v92, v92
	v_rcp_f32_e32 v97, v93
	v_add_f32_e32 v92, 1.0, v92
	v_rcp_f32_e32 v92, v92
	v_lshl_add_u64 v[94:95], s[12:13], 0, v[108:109]
	v_lshl_add_u64 v[94:95], v[94:95], 0, s[18:19]
	v_lshl_add_u64 v[124:125], v[94:95], 0, v[116:117]
	v_mul_f32_e32 v92, 0xc1000000, v92
	v_mul_f32_e32 v92, v123, v92
	v_mul_f32_e32 v92, 0x3fb8aa3b, v92
	v_exp_f32_e32 v115, v92
	global_store_dword v[124:125], v96, off
	ds_read_b32 v96, v241 offset:816
	v_fma_f32 v92, -v115, v115, 1.0
	v_max_f32_e32 v92, 0, v92
	s_nop 0
	s_nop 0
	s_nop 0
	s_nop 1
	s_nop 1
	v_sqrt_f32_e32 v120, v92
	s_nop 0
	v_or_b32_e32 v92, 3, v110
	v_ashrrev_i32_e32 v93, 31, v92
	v_lshlrev_b64 v[110:111], 12, v[92:93]
	v_lshl_add_u64 v[92:93], v[118:119], 0, v[110:111]
	s_waitcnt vmcnt(18)
	v_mov_b32_e32 v92, v151
	v_mul_f32_e32 v118, v115, v92
	v_mul_f32_e32 v92, v97, v120
	s_waitcnt lgkmcnt(0)
	v_fmac_f32_e32 v118, v92, v96
	v_or_b32_e32 v92, 3, v114
	v_ashrrev_i32_e32 v93, 31, v92
	v_lshlrev_b64 v[96:97], 10, v[92:93]
	v_or_b32_e32 v92, v96, v122
	v_mov_b32_e32 v93, v97
	v_lshlrev_b64 v[92:93], 1, v[92:93]
	v_lshl_add_u64 v[114:115], v[92:93], 1, s[62:63]
	v_cvt_pk_bf16_f32 v119, v118, v1
	v_lshl_add_u64 v[92:93], s[12:13], 0, v[110:111]
	v_lshl_add_u64 v[92:93], v[92:93], 0, s[18:19]
	global_store_dword v[114:115], v119, off
	v_lshl_add_u64 v[114:115], v[92:93], 0, v[116:117]
	global_store_dword v[114:115], v118, off
	v_add_u32_e32 v114, 64, v232
	ds_read2st64_b32 v[118:119], v114 offset0:39 offset1:40
	ds_read_b32 v121, v232 offset:10560
	v_add_lshl_u32 v114, s75, v223, 2
	v_mov_b32_e32 v115, v1
	v_lshl_add_u64 v[114:115], s[14:15], 0, v[114:115]
	s_waitcnt lgkmcnt(1)
	v_add_f32_e32 v86, v86, v118
	v_mul_f32_e32 v86, 0xbfb8aa3b, v86
	v_exp_f32_e32 v86, v86
	v_lshl_add_u64 v[106:107], v[114:115], 0, v[106:107]
	v_add_f32_e32 v82, v82, v119
	v_mul_f32_e32 v82, 0xbfb8aa3b, v82
	v_add_f32_e32 v86, 1.0, v86
	v_rcp_f32_e32 v86, v86
	v_exp_f32_e32 v82, v82
	ds_read_b32 v116, v241 offset:64
	v_or_b32_e32 v120, s75, v233
	v_mul_f32_e32 v86, 0xc1000000, v86
	s_waitcnt lgkmcnt(1)
	v_mul_f32_e32 v86, v121, v86
	v_mul_f32_e32 v86, 0x3fb8aa3b, v86
	v_exp_f32_e32 v86, v86
	v_add_f32_e32 v82, 1.0, v82
	v_rcp_f32_e32 v82, v82
	v_add_f32_e32 v83, v83, v119
	v_fma_f32 v117, -v86, v86, 1.0
	v_max_f32_e32 v117, 0, v117
	v_mul_f32_e32 v83, 0xbfb8aa3b, v83
	v_exp_f32_e32 v83, v83
	v_add_f32_e32 v84, v84, v119
	v_mul_f32_e32 v84, 0xbfb8aa3b, v84
	v_add_f32_e32 v83, 1.0, v83
	v_exp_f32_e32 v84, v84
	v_add_f32_e32 v85, v85, v119
	v_add_f32_e32 v84, 1.0, v84
	v_rcp_f32_e32 v84, v84
	v_sqrt_f32_e32 v117, v117
	s_nop 0
	v_mul_f32_e32 v82, v82, v117
	s_waitcnt lgkmcnt(0)
; __device__ __forceinline__ unsigned cvt_pk_bf16(float lo, float hi) { unsigned r; asm volatile("v_cvt_pk_bf16_f32 %0, %1, %2" : "=v"(r) : "v"(lo), "v"(hi)); return r; }
; __device__ __forceinline__ float sigmoidf_(float x) { return __builtin_amdgcn_rcpf(1.0f + __expf(-x)); }
; __device__ __forceinline__ void scan_phase(KP p, int l, LAS unsigned char* lds) {
;     ...
; #pragma unroll
;             for (int n = 0; n < 4; ++n) {
;                 const int cc = 16 * n + fr, ch = hc0 + cc;
;                 const float ba = CST[5 * 64 + cc], bx = CST[6 * 64 + cc], sp = CST[7 * 64 + cc];
; #pragma unroll
;                 for (int j = 0; j < 4; ++j) {
;                     const float xc = XC[(4 * fq + j) * 68 + cc];
;                     const float r = sigmoidf_(ar[n][j] + ba), ig = sigmoidf_(ai[n][j] + bx);
;                     const float a = __expf(-8.0f * r * sp);
;                     const float mult = sqrtf(fmaxf(1.0f - a * a, 0.f));
;                     const int sb = m0 - MP + 4 * fq + j;
;                     const float h0 = p->in[4][(size_t)(l * MS + sb) * D + ch];
;                     const float h = a * h0 + mult * ig * xc;
;                     const size_t o = (size_t)(m0 + 4 * fq + j) * D + ch; HLOC[o] = (bf16_t)(cvt_pk_bf16(h, 0.f) & 0xffffu); PCUM[o] = 0;
;                     p->out[O_SRG + (size_t)(l * MS + sb) * D + ch] = h; }
	v_mul_f32_e32 v82, v116, v82
	v_or_b32_e32 v116, v102, v120
	v_mov_b32_e32 v117, v103
	v_lshlrev_b64 v[116:117], 1, v[116:117]
	v_mul_f32_e32 v85, 0xbfb8aa3b, v85
	v_exp_f32_e32 v85, v85
	s_waitcnt vmcnt(19)
	v_mov_b32_e32 v122, v152
	v_fmac_f32_e32 v82, v122, v86
	v_lshl_add_u64 v[122:123], v[116:117], 1, s[62:63]
	v_cvt_pk_bf16_f32 v86, v82, v1
	v_lshlrev_b32_e32 v116, 2, v120
	v_mov_b32_e32 v117, v1
	global_store_dword v[122:123], v86, off
	v_lshl_add_u64 v[122:123], v[98:99], 0, v[116:117]
	global_store_dword v[122:123], v82, off
	v_add_f32_e32 v82, v87, v118
	v_mul_f32_e32 v82, 0xbfb8aa3b, v82
	v_exp_f32_e32 v82, v82
	v_rcp_f32_e32 v87, v83
	ds_read_b32 v86, v241 offset:336
	v_add_f32_e32 v85, 1.0, v85
	v_add_f32_e32 v82, 1.0, v82
	v_rcp_f32_e32 v82, v82
	s_nop 0
	v_mul_f32_e32 v82, 0xc1000000, v82
	v_mul_f32_e32 v82, v121, v82
	v_mul_f32_e32 v82, 0x3fb8aa3b, v82
	v_exp_f32_e32 v122, v82
	s_nop 0
	v_fma_f32 v82, -v122, v122, 1.0
	v_max_f32_e32 v82, 0, v82
	s_nop 0
	s_nop 0
	s_nop 0
	s_nop 1
	s_nop 1
	v_sqrt_f32_e32 v123, v82
	s_nop 0
	v_lshl_add_u64 v[82:83], v[114:115], 0, v[112:113]
	v_mul_f32_e32 v87, v87, v123
	s_waitcnt lgkmcnt(0)
	v_mul_f32_e32 v123, v86, v87
	v_or_b32_e32 v86, v100, v120
	v_mov_b32_e32 v87, v101
	v_lshlrev_b64 v[86:87], 1, v[86:87]
	s_waitcnt vmcnt(20)
	v_mov_b32_e32 v112, v153
	v_fmac_f32_e32 v123, v122, v112
	v_lshl_add_u64 v[112:113], v[86:87], 1, s[62:63]
	v_cvt_pk_bf16_f32 v122, v123, v1
	v_lshl_add_u64 v[86:87], v[90:91], 0, v[116:117]
	global_store_dword v[86:87], v123, off
	v_add_f32_e32 v86, v88, v118
	v_mul_f32_e32 v86, 0xbfb8aa3b, v86
	v_exp_f32_e32 v86, v86
	global_store_dword v[112:113], v122, off
	ds_read_b32 v112, v241 offset:608
	v_add_f32_e32 v86, 1.0, v86
	v_rcp_f32_e32 v86, v86
	s_nop 0
	v_mul_f32_e32 v86, 0xc1000000, v86
	v_mul_f32_e32 v86, v121, v86
	v_mul_f32_e32 v86, 0x3fb8aa3b, v86
	v_exp_f32_e32 v88, v86
	s_nop 0
	v_fma_f32 v86, -v88, v88, 1.0
	v_max_f32_e32 v86, 0, v86
	s_nop 0
	s_nop 0
	s_nop 0
	s_nop 1
	s_nop 1
	v_sqrt_f32_e32 v113, v86
	s_nop 0
	v_lshl_add_u64 v[86:87], v[114:115], 0, v[108:109]
	v_mov_b32_e32 v109, v105
	v_mul_f32_e32 v84, v84, v113
	s_waitcnt vmcnt(21)
	v_mov_b32_e32 v108, v154
	v_mul_f32_e32 v88, v88, v108
	v_or_b32_e32 v108, v104, v120
	v_lshlrev_b64 v[108:109], 1, v[108:109]
	s_waitcnt lgkmcnt(0)
	v_fmac_f32_e32 v88, v84, v112
	v_cvt_pk_bf16_f32 v84, v88, v1
	v_lshl_add_u64 v[112:113], v[108:109], 1, s[62:63]
	global_store_dword v[112:113], v84, off
	v_add_f32_e32 v84, v89, v118
	v_mul_f32_e32 v84, 0xbfb8aa3b, v84
	v_exp_f32_e32 v84, v84
	v_lshl_add_u64 v[108:109], v[94:95], 0, v[116:117]
	v_add_f32_e32 v84, 1.0, v84
	v_rcp_f32_e32 v84, v84
	global_store_dword v[108:109], v88, off
	v_rcp_f32_e32 v89, v85
	ds_read_b32 v88, v241 offset:880
	v_mul_f32_e32 v84, 0xc1000000, v84
	v_mul_f32_e32 v84, v121, v84
	v_mul_f32_e32 v84, 0x3fb8aa3b, v84
	v_exp_f32_e32 v108, v84
	s_nop 0
	v_fma_f32 v84, -v108, v108, 1.0
	v_max_f32_e32 v84, 0, v84
	s_nop 0
	s_nop 0
	s_nop 0
	s_nop 1
	s_nop 1
	v_sqrt_f32_e32 v109, v84
	s_nop 0
	v_lshl_add_u64 v[84:85], v[114:115], 0, v[110:111]
	v_mul_f32_e32 v89, v89, v109
	s_waitcnt vmcnt(22)
	v_mov_b32_e32 v110, v155
	v_mul_f32_e32 v110, v108, v110
	s_waitcnt lgkmcnt(0)
	v_fmac_f32_e32 v110, v89, v88
	v_or_b32_e32 v88, v96, v120
	v_mov_b32_e32 v89, v97
	v_lshlrev_b64 v[88:89], 1, v[88:89]
	v_lshl_add_u64 v[108:109], v[88:89], 1, s[62:63]
	v_cvt_pk_bf16_f32 v111, v110, v1
	v_lshl_add_u64 v[88:89], v[92:93], 0, v[116:117]
	global_store_dword v[108:109], v111, off
	global_store_dword v[88:89], v110, off
	v_add_u32_e32 v88, 0x80, v232
	ds_read2st64_b32 v[108:109], v88 offset0:39 offset1:40
	ds_read_b32 v111, v232 offset:10624
	ds_read_b32 v88, v241 offset:128
	v_or_b32_e32 v110, s75, v234
	s_waitcnt lgkmcnt(2)
	v_add_f32_e32 v78, v78, v108
	v_mul_f32_e32 v78, 0xbfb8aa3b, v78
	v_exp_f32_e32 v78, v78
	v_add_f32_e32 v74, v74, v109
	v_mul_f32_e32 v74, 0xbfb8aa3b, v74
	v_exp_f32_e32 v74, v74
	v_add_f32_e32 v78, 1.0, v78
	v_rcp_f32_e32 v78, v78
	v_add_f32_e32 v75, v75, v109
	v_add_f32_e32 v74, 1.0, v74
	v_rcp_f32_e32 v74, v74
	v_mul_f32_e32 v78, 0xc1000000, v78
	s_waitcnt lgkmcnt(1)
	v_mul_f32_e32 v78, v111, v78
	v_mul_f32_e32 v78, 0x3fb8aa3b, v78
	v_exp_f32_e32 v78, v78
	v_mul_f32_e32 v75, 0xbfb8aa3b, v75
	v_exp_f32_e32 v75, v75
	v_add_f32_e32 v76, v76, v109
	v_fma_f32 v89, -v78, v78, 1.0
	v_max_f32_e32 v89, 0, v89
	v_add_f32_e32 v75, 1.0, v75
	v_rcp_f32_e32 v75, v75
	v_mul_f32_e32 v76, 0xbfb8aa3b, v76
	v_exp_f32_e32 v76, v76
	s_nop 0
	v_add_f32_e32 v76, 1.0, v76
	v_rcp_f32_e32 v76, v76
	s_nop 0
	s_nop 1
	v_sqrt_f32_e32 v89, v89
	s_nop 0
	v_mul_f32_e32 v74, v74, v89
	s_waitcnt lgkmcnt(0)
	v_mul_f32_e32 v74, v88, v74
	v_or_b32_e32 v88, v102, v110
	v_mov_b32_e32 v89, v103
	v_lshlrev_b64 v[88:89], 1, v[88:89]
	s_waitcnt vmcnt(23)
	v_mov_b32_e32 v112, v156
	v_fmac_f32_e32 v74, v112, v78
	v_cvt_pk_bf16_f32 v78, v74, v1
	v_lshl_add_u64 v[112:113], v[88:89], 1, s[62:63]
	global_store_dword v[112:113], v78, off
	v_add_f32_e32 v78, v79, v108
	v_mul_f32_e32 v78, 0xbfb8aa3b, v78
	v_exp_f32_e32 v78, v78
	v_lshlrev_b32_e32 v88, 2, v110
	v_add_f32_e32 v78, 1.0, v78
	v_rcp_f32_e32 v78, v78
	v_mov_b32_e32 v89, v1
	v_lshl_add_u64 v[112:113], v[98:99], 0, v[88:89]
	global_store_dword v[112:113], v74, off
	v_mul_f32_e32 v78, 0xc1000000, v78
	v_mul_f32_e32 v78, v111, v78
	v_mul_f32_e32 v78, 0x3fb8aa3b, v78
	v_exp_f32_e32 v78, v78
	ds_read_b32 v74, v241 offset:400
	v_fma_f32 v79, -v78, v78, 1.0
	v_max_f32_e32 v79, 0, v79
	s_nop 0
	s_nop 0
	s_nop 0
	s_nop 1
	s_nop 1
	v_sqrt_f32_e32 v79, v79
	s_nop 0
	v_mul_f32_e32 v75, v75, v79
	s_waitcnt lgkmcnt(0)
; __device__ __forceinline__ unsigned cvt_pk_bf16(float lo, float hi) { unsigned r; asm volatile("v_cvt_pk_bf16_f32 %0, %1, %2" : "=v"(r) : "v"(lo), "v"(hi)); return r; }
; __device__ __forceinline__ float sigmoidf_(float x) { return __builtin_amdgcn_rcpf(1.0f + __expf(-x)); }
; __device__ __forceinline__ void scan_phase(KP p, int l, LAS unsigned char* lds) {
;     ...
; #pragma unroll
;             for (int n = 0; n < 4; ++n) {
;                 const int cc = 16 * n + fr, ch = hc0 + cc;
;                 const float ba = CST[5 * 64 + cc], bx = CST[6 * 64 + cc], sp = CST[7 * 64 + cc];
; #pragma unroll
;                 for (int j = 0; j < 4; ++j) {
;                     const float xc = XC[(4 * fq + j) * 68 + cc];
;                     const float r = sigmoidf_(ar[n][j] + ba), ig = sigmoidf_(ai[n][j] + bx);
;                     const float a = __expf(-8.0f * r * sp);
;                     const float mult = sqrtf(fmaxf(1.0f - a * a, 0.f));
;                     const int sb = m0 - MP + 4 * fq + j;
;                     const float h0 = p->in[4][(size_t)(l * MS + sb) * D + ch];
;                     const float h = a * h0 + mult * ig * xc;
;                     const size_t o = (size_t)(m0 + 4 * fq + j) * D + ch; HLOC[o] = (bf16_t)(cvt_pk_bf16(h, 0.f) & 0xffffu); PCUM[o] = 0;
;                     p->out[O_SRG + (size_t)(l * MS + sb) * D + ch] = h; }
;             }
;         }
;     }
	v_mul_f32_e32 v113, v74, v75
	v_or_b32_e32 v74, v100, v110
	v_mov_b32_e32 v75, v101
	v_lshlrev_b64 v[74:75], 1, v[74:75]
	s_waitcnt vmcnt(24)
	v_mov_b32_e32 v112, v157
	v_fmac_f32_e32 v113, v78, v112
	v_lshl_add_u64 v[78:79], v[74:75], 1, s[62:63]
	v_cvt_pk_bf16_f32 v112, v113, v1
	v_lshl_add_u64 v[74:75], v[90:91], 0, v[88:89]
	global_store_dword v[74:75], v113, off
	v_add_f32_e32 v75, v80, v108
	v_mul_f32_e32 v75, 0xbfb8aa3b, v75
	v_exp_f32_e32 v75, v75
	global_store_dword v[78:79], v112, off
	ds_read_b32 v74, v241 offset:672
	v_add_f32_e32 v75, 1.0, v75
	v_rcp_f32_e32 v75, v75
	s_nop 0
	v_mul_f32_e32 v75, 0xc1000000, v75
	v_mul_f32_e32 v75, v111, v75
	v_mul_f32_e32 v75, 0x3fb8aa3b, v75
	v_exp_f32_e32 v75, v75
	s_nop 0
	v_fma_f32 v78, -v75, v75, 1.0
	v_max_f32_e32 v78, 0, v78
	s_nop 0
	s_nop 0
	s_nop 0
	s_nop 1
	s_nop 1
	v_sqrt_f32_e32 v78, v78
	s_nop 0
	s_waitcnt vmcnt(25)
	v_mov_b32_e32 v79, v158
	v_mul_f32_e32 v80, v75, v79
	v_mul_f32_e32 v75, v76, v78
	s_waitcnt lgkmcnt(0)
	v_fmac_f32_e32 v80, v75, v74
	v_or_b32_e32 v74, v104, v110
	v_mov_b32_e32 v75, v105
	v_lshlrev_b64 v[74:75], 1, v[74:75]
	v_lshl_add_u64 v[78:79], v[74:75], 1, s[62:63]
	v_cvt_pk_bf16_f32 v76, v80, v1
	v_lshl_add_u64 v[74:75], v[94:95], 0, v[88:89]
	global_store_dword v[74:75], v80, off
	v_add_f32_e32 v75, v81, v108
	v_mul_f32_e32 v75, 0xbfb8aa3b, v75
	v_exp_f32_e32 v75, v75
	global_store_dword v[78:79], v76, off
	v_add_f32_e32 v76, v77, v109
	v_mul_f32_e32 v76, 0xbfb8aa3b, v76
	v_add_f32_e32 v75, 1.0, v75
	v_rcp_f32_e32 v75, v75
	v_exp_f32_e32 v76, v76
	ds_read_b32 v74, v241 offset:944
	v_mul_f32_e32 v75, 0xc1000000, v75
	v_mul_f32_e32 v75, v111, v75
	v_mul_f32_e32 v75, 0x3fb8aa3b, v75
	v_exp_f32_e32 v75, v75
	v_add_f32_e32 v76, 1.0, v76
	v_rcp_f32_e32 v76, v76
	v_fma_f32 v77, -v75, v75, 1.0
	v_max_f32_e32 v77, 0, v77
	s_nop 0
	s_nop 0
	s_nop 0
	s_nop 1
	s_nop 1
	v_sqrt_f32_e32 v77, v77
	s_nop 0
	s_waitcnt vmcnt(26)
	v_mov_b32_e32 v78, v159
	v_mul_f32_e32 v78, v75, v78
	v_mul_f32_e32 v75, v76, v77
	s_waitcnt lgkmcnt(0)
	v_fmac_f32_e32 v78, v75, v74
	v_or_b32_e32 v74, v96, v110
	v_mov_b32_e32 v75, v97
	v_lshlrev_b64 v[74:75], 1, v[74:75]
	v_lshl_add_u64 v[76:77], v[74:75], 1, s[62:63]
	v_cvt_pk_bf16_f32 v79, v78, v1
	v_lshl_add_u64 v[74:75], v[92:93], 0, v[88:89]
	global_store_dword v[76:77], v79, off
	global_store_dword v[74:75], v78, off
	v_add_u32_e32 v74, 0xc0, v232
	ds_read2st64_b32 v[76:77], v74 offset0:39 offset1:40
	ds_read_b32 v79, v232 offset:10688
	ds_read_b32 v74, v241 offset:192
	v_or_b32_e32 v78, s75, v235
	v_or_b32_e32 v102, v102, v78
	s_waitcnt lgkmcnt(2)
	v_add_f32_e32 v70, v70, v76
	v_mul_f32_e32 v70, 0xbfb8aa3b, v70
	v_exp_f32_e32 v70, v70
	v_add_f32_e32 v66, v66, v77
	v_mul_f32_e32 v66, 0xbfb8aa3b, v66
	v_exp_f32_e32 v66, v66
	v_add_f32_e32 v70, 1.0, v70
	v_rcp_f32_e32 v70, v70
	v_add_f32_e32 v67, v67, v77
	v_add_f32_e32 v66, 1.0, v66
	v_rcp_f32_e32 v66, v66
	v_mul_f32_e32 v70, 0xc1000000, v70
	s_waitcnt lgkmcnt(1)
	v_mul_f32_e32 v70, v79, v70
	v_mul_f32_e32 v70, 0x3fb8aa3b, v70
	v_exp_f32_e32 v70, v70
	v_mul_f32_e32 v67, 0xbfb8aa3b, v67
	v_exp_f32_e32 v67, v67
	v_or_b32_e32 v100, v100, v78
	v_fma_f32 v75, -v70, v70, 1.0
	v_max_f32_e32 v75, 0, v75
	v_add_f32_e32 v67, 1.0, v67
	v_rcp_f32_e32 v67, v67
	v_add_f32_e32 v68, v68, v77
	v_mul_f32_e32 v68, 0xbfb8aa3b, v68
	v_exp_f32_e32 v68, v68
	s_nop 0
	v_add_f32_e32 v68, 1.0, v68
	v_rcp_f32_e32 v68, v68
	v_or_b32_e32 v104, v104, v78
	v_or_b32_e32 v96, v96, v78
	v_sqrt_f32_e32 v75, v75
	s_nop 0
	v_mul_f32_e32 v66, v66, v75
	s_waitcnt lgkmcnt(0)
	v_mul_f32_e32 v66, v74, v66
	v_lshlrev_b64 v[74:75], 1, v[102:103]
	s_waitcnt vmcnt(27)
	v_mov_b32_e32 v80, v160
	v_fmac_f32_e32 v66, v80, v70
	v_cvt_pk_bf16_f32 v70, v66, v1
	v_lshl_add_u64 v[80:81], v[74:75], 1, s[62:63]
	global_store_dword v[80:81], v70, off
	v_add_f32_e32 v70, v71, v76
	v_mul_f32_e32 v70, 0xbfb8aa3b, v70
	v_exp_f32_e32 v70, v70
	v_lshlrev_b32_e32 v74, 2, v78
	v_add_f32_e32 v70, 1.0, v70
	v_rcp_f32_e32 v70, v70
	v_mov_b32_e32 v75, v1
	v_lshl_add_u64 v[80:81], v[98:99], 0, v[74:75]
	global_store_dword v[80:81], v66, off
	v_mul_f32_e32 v70, 0xc1000000, v70
	v_mul_f32_e32 v70, v79, v70
	v_mul_f32_e32 v70, 0x3fb8aa3b, v70
	v_exp_f32_e32 v70, v70
	ds_read_b32 v66, v241 offset:464
	v_fma_f32 v71, -v70, v70, 1.0
	v_max_f32_e32 v71, 0, v71
	s_nop 0
	s_nop 0
	s_nop 0
	s_nop 1
	s_nop 1
	v_sqrt_f32_e32 v71, v71
	s_nop 0
	v_mul_f32_e32 v67, v67, v71
	s_waitcnt lgkmcnt(0)
	v_mul_f32_e32 v81, v66, v67
	v_lshlrev_b64 v[66:67], 1, v[100:101]
	s_waitcnt vmcnt(28)
	v_mov_b32_e32 v80, v161
	v_fmac_f32_e32 v81, v70, v80
	v_lshl_add_u64 v[70:71], v[66:67], 1, s[62:63]
	v_cvt_pk_bf16_f32 v80, v81, v1
	v_lshl_add_u64 v[66:67], v[90:91], 0, v[74:75]
	global_store_dword v[66:67], v81, off
	v_add_f32_e32 v67, v72, v76
	v_mul_f32_e32 v67, 0xbfb8aa3b, v67
	v_exp_f32_e32 v67, v67
	global_store_dword v[70:71], v80, off
	ds_read_b32 v66, v241 offset:736
	v_add_f32_e32 v67, 1.0, v67
	v_rcp_f32_e32 v67, v67
	s_nop 0
	v_mul_f32_e32 v67, 0xc1000000, v67
	v_mul_f32_e32 v67, v79, v67
	v_mul_f32_e32 v67, 0x3fb8aa3b, v67
	v_exp_f32_e32 v67, v67
	s_nop 0
	v_fma_f32 v70, -v67, v67, 1.0
	v_max_f32_e32 v70, 0, v70
	s_nop 0
	s_nop 0
	s_nop 0
	s_nop 1
	s_nop 1
	v_sqrt_f32_e32 v70, v70
	s_nop 0
	s_waitcnt vmcnt(29)
	v_mov_b32_e32 v71, v162
	v_mul_f32_e32 v72, v67, v71
	v_mul_f32_e32 v67, v68, v70
	s_waitcnt lgkmcnt(0)
	v_fmac_f32_e32 v72, v67, v66
	v_lshlrev_b64 v[66:67], 1, v[104:105]
	v_lshl_add_u64 v[70:71], v[66:67], 1, s[62:63]
	v_cvt_pk_bf16_f32 v68, v72, v1
	v_lshl_add_u64 v[66:67], v[94:95], 0, v[74:75]
	global_store_dword v[66:67], v72, off
	v_add_f32_e32 v67, v73, v76
	v_mul_f32_e32 v67, 0xbfb8aa3b, v67
	v_exp_f32_e32 v67, v67
	global_store_dword v[70:71], v68, off
	v_add_f32_e32 v68, v69, v77
	v_mul_f32_e32 v68, 0xbfb8aa3b, v68
	v_add_f32_e32 v67, 1.0, v67
	v_rcp_f32_e32 v67, v67
	v_exp_f32_e32 v68, v68
	ds_read_b32 v66, v241 offset:1008
	v_mul_f32_e32 v67, 0xc1000000, v67
	v_mul_f32_e32 v67, v79, v67
	v_mul_f32_e32 v67, 0x3fb8aa3b, v67
	v_exp_f32_e32 v67, v67
	v_add_f32_e32 v68, 1.0, v68
	v_rcp_f32_e32 v68, v68
	v_fma_f32 v69, -v67, v67, 1.0
	v_max_f32_e32 v69, 0, v69
	s_nop 0
	s_nop 0
	s_nop 0
	s_nop 1
	s_nop 1
	v_sqrt_f32_e32 v69, v69
	s_nop 0
	s_waitcnt vmcnt(30)
	v_mov_b32_e32 v70, v163
	v_mul_f32_e32 v70, v67, v70
	v_mul_f32_e32 v67, v68, v69
	s_waitcnt lgkmcnt(0)
	v_fmac_f32_e32 v70, v67, v66
	v_lshlrev_b64 v[66:67], 1, v[96:97]
	v_lshl_add_u64 v[68:69], v[66:67], 1, s[62:63]
	v_cvt_pk_bf16_f32 v71, v70, v1
	v_lshl_add_u64 v[66:67], v[92:93], 0, v[74:75]
	global_store_dword v[68:69], v71, off
	global_store_dword v[66:67], v70, off
	s_cbranch_execnz .LBB0_330
	s_branch .LBB0_334
